# up-GEMM K-loop load segments: first two LDS-DMA stages issued before the ds_read fragment loads
# speedup vs baseline: 1.0001x; 1.0001x over previous
; #define PG8_STAGE(bufoff, gbase, voff) do { _Pragma("unroll") for (int _i = 0; _i < 2; ++_i) \
;         __builtin_amdgcn_global_load_lds((const unsigned*)((const char*)(gbase) + (voff)[_i]), (PG8_LAS unsigned*)(lds + (bufoff) + ldsw + _i * 8192), 16, 0, 0); } while (0)
; #define PG8_LDA(dst, b, h) do { _Pragma("unroll") for (int m = 0; m < 4; ++m) _Pragma("unroll") for (int k = 0; k < 2; ++k) dst[m][k] = *(const PG8_LAS bf16x8*)(lds + PG8_SA(b, h) + aoff + m * 2048 + k * 1024); } while (0)
; #define PG8_LDB(dst, b, h) do { _Pragma("unroll") for (int n = 0; n < 2; ++n) _Pragma("unroll") for (int k = 0; k < 2; ++k) dst[n][k] = *(const PG8_LAS bf16x8*)(lds + PG8_SB(b, h) + boff + n * 2048 + k * 1024); } while (0)
; #define PG8_MMA(ai, bj, At, Bt) do { __builtin_amdgcn_s_setprio(1); _Pragma("unroll") for (int m = 0; m < 4; ++m) _Pragma("unroll") for (int n = 0; n < 2; ++n) _Pragma("unroll") for (int k = 0; k < 2; ++k) \
;         acc[ai][bj][m][n] = __builtin_amdgcn_mfma_f32_16x16x32_bf16(Bt[n][k], At[m][k], acc[ai][bj][m][n], 0, 0, 0); __builtin_amdgcn_s_setprio(0); } while (0)
; #define PG8_WAIT_V(n) asm volatile("s_waitcnt vmcnt(" #n ")" ::: "memory")
; #define PG8_BAR __builtin_amdgcn_s_barrier()
; template <class Epi, class Sched, bool ALIGN_EPI = false, bool SP2 = false>
; __device__ __forceinline__ void gemm_phase(PG8_LAS unsigned char* lds, const Gemm g, const Sched& S, const Epi& E) {
;     ...
;         for (int t = 0; t < nt; t += 2) {
;             const bool last = (t == nt - 2);
;             const char* a1 = cA + (size_t)(t + 1) * kstep;
;             const char* a2 = last ? nA : cA + (size_t)(t + 2) * kstep; const char* b2 = last ? nB : cB + (size_t)(t + 2) * kstep;
;             const char* a3 = a2 + kstep; const char* b3 = b2 + kstep;
;             if (last && has_next) S.a_ready(nxt);
;             if constexpr (SP2) {
;             PG8_LDB(B0, 0, 0); PG8_LDB(B1, 0, 1); PG8_SCHED; PG8_LDA(At, 0, 0); PG8_STAGE(PG8_SA(1, 1), a1 + hstepA, voffA);
;             PG8_WAIT_V(8); PG8_WAIT_L(0); PG8_BAR; PG8_MMA(0, 0, At, B0); PG8_MMA(0, 1, At, B1); PG8_BAR; PG8_SCHED;
;             PG8_LDA(At, 0, 1); PG8_STAGE(PG8_SB(0, 0), b2, voffB); PG8_STAGE(PG8_SB(0, 1), b2 + hstepB, voffB); PG8_STAGE(PG8_SA(0, 0), a2, voffA);
;             PG8_WAIT_V(8); PG8_WAIT_L(0); PG8_BAR; PG8_MMA(1, 0, At, B0); PG8_MMA(1, 1, At, B1); PG8_BAR; PG8_SCHED;
.LBB0_1211:
	s_ashr_i32 s29, s28, 31
	s_lshl_b64 s[20:21], s[28:29], 19
	s_add_u32 s30, s10, s20
	s_addc_u32 s31, s11, s21
	s_and_b64 s[20:21], s[42:43], exec
	s_cselect_b32 s29, s31, s9
	s_cselect_b32 s62, s30, s8
	s_ashr_i32 s19, s18, 31
	s_lshl_b64 s[20:21], s[18:19], 19
	s_add_u32 s34, s45, s20
	s_addc_u32 s35, s46, s21
	s_and_b64 s[20:21], s[42:43], exec
	s_cselect_b32 s19, s35, s37
	s_cselect_b32 s63, s34, s36
	s_add_u32 s8, s8, 0x40080
	s_addc_u32 s9, s9, 0
	s_add_u32 s70, s36, 0x100
	s_addc_u32 s71, s37, 0
	s_mov_b32 s76, -2
	s_add_u32 s20, s8, 0xfffc0080
	s_addc_u32 s21, s9, -1
	s_add_i32 s77, 0, 0x10000
	s_cmp_eq_u32 s76, 12
	s_cselect_b32 s39, s29, s21
	s_cselect_b32 s38, s62, s20
	s_cselect_b32 s37, s19, s71
	s_cselect_b32 s36, s63, s70
	s_add_i32 s78, 0, 0x14000
	v_lshl_add_u64 v[204:205], s[8:9], 0, v[136:137]
	s_add_i32 m0, s52, 0xc000
	s_nop 0
	global_load_lds_dwordx4 v[204:205], off
	v_lshl_add_u64 v[204:205], s[8:9], 0, v[138:139]
	s_add_i32 m0, s52, 0xe000
	s_nop 0
	global_load_lds_dwordx4 v[204:205], off
	v_add_u32_e32 v149, s77, v146
	ds_read_b128 v[140:143], v149
	ds_read_b128 v[150:153], v149 offset:1024
	ds_read_b128 v[154:157], v149 offset:2048
	ds_read_b128 v[158:161], v149 offset:3072
	v_add_u32_e32 v149, s78, v146
	ds_read_b128 v[162:165], v149
	ds_read_b128 v[166:169], v149 offset:1024
	ds_read_b128 v[170:173], v149 offset:2048
	ds_read_b128 v[174:177], v149 offset:3072
	ds_read_b128 v[178:181], v148
	ds_read_b128 v[182:185], v148 offset:1024
	ds_read_b128 v[186:189], v148 offset:2048
	ds_read_b128 v[190:193], v148 offset:3072
	ds_read_b128 v[194:197], v148 offset:4096
	ds_read_b128 v[198:201], v148 offset:5120
	ds_read_b128 v[208:211], v148 offset:6144
	ds_read_b128 v[212:215], v148 offset:7168
	s_waitcnt vmcnt(8)
	s_waitcnt lgkmcnt(0)
	s_barrier
	s_setprio 1
	s_waitcnt lgkmcnt(0)
	v_mfma_f32_16x16x32_bf16 v[126:129], v[140:143], v[178:181], 0
	v_mfma_f32_16x16x32_bf16 v[118:121], v[154:157], v[178:181], 0
	v_mfma_f32_16x16x32_bf16 v[110:113], v[140:143], v[186:189], 0
	v_mfma_f32_16x16x32_bf16 v[102:105], v[154:157], v[186:189], 0
	v_mfma_f32_16x16x32_bf16 v[94:97], v[140:143], v[194:197], 0
	v_mfma_f32_16x16x32_bf16 v[86:89], v[154:157], v[194:197], 0
	v_mfma_f32_16x16x32_bf16 v[78:81], v[140:143], v[208:211], 0
	v_mfma_f32_16x16x32_bf16 v[70:73], v[154:157], v[208:211], 0
	v_mfma_f32_16x16x32_bf16 v[126:129], v[150:153], v[182:185], v[126:129]
	v_mfma_f32_16x16x32_bf16 v[118:121], v[158:161], v[182:185], v[118:121]
	v_mfma_f32_16x16x32_bf16 v[110:113], v[150:153], v[190:193], v[110:113]
	v_mfma_f32_16x16x32_bf16 v[102:105], v[158:161], v[190:193], v[102:105]
	v_mfma_f32_16x16x32_bf16 v[94:97], v[150:153], v[198:201], v[94:97]
	v_mfma_f32_16x16x32_bf16 v[86:89], v[158:161], v[198:201], v[86:89]
	v_mfma_f32_16x16x32_bf16 v[78:81], v[150:153], v[212:215], v[78:81]
	v_mfma_f32_16x16x32_bf16 v[70:73], v[158:161], v[212:215], v[70:73]
	s_setprio 0
	s_setprio 1
	v_mfma_f32_16x16x32_bf16 v[122:125], v[162:165], v[178:181], 0
	v_mfma_f32_16x16x32_bf16 v[114:117], v[170:173], v[178:181], 0
	v_mfma_f32_16x16x32_bf16 v[106:109], v[162:165], v[186:189], 0
	v_mfma_f32_16x16x32_bf16 v[98:101], v[170:173], v[186:189], 0
	v_mfma_f32_16x16x32_bf16 v[90:93], v[162:165], v[194:197], 0
	v_mfma_f32_16x16x32_bf16 v[82:85], v[170:173], v[194:197], 0
	v_mfma_f32_16x16x32_bf16 v[74:77], v[162:165], v[208:211], 0
	v_mfma_f32_16x16x32_bf16 v[66:69], v[170:173], v[208:211], 0
	v_mfma_f32_16x16x32_bf16 v[122:125], v[166:169], v[182:185], v[122:125]
	v_mfma_f32_16x16x32_bf16 v[114:117], v[174:177], v[182:185], v[114:117]
	v_mfma_f32_16x16x32_bf16 v[106:109], v[166:169], v[190:193], v[106:109]
	v_mfma_f32_16x16x32_bf16 v[98:101], v[174:177], v[190:193], v[98:101]
	v_mfma_f32_16x16x32_bf16 v[90:93], v[166:169], v[198:201], v[90:93]
	v_mfma_f32_16x16x32_bf16 v[82:85], v[174:177], v[198:201], v[82:85]
	v_mfma_f32_16x16x32_bf16 v[74:77], v[166:169], v[212:215], v[74:77]
	v_mfma_f32_16x16x32_bf16 v[66:69], v[174:177], v[212:215], v[66:69]
	s_setprio 0
	s_barrier
	s_add_i32 s20, s77, s47
	v_lshl_add_u64 v[204:205], s[36:37], 0, v[0:1]
	s_mov_b32 m0, s20
	s_nop 0
	global_load_lds_dwordx4 v[204:205], off
	s_add_i32 m0, s20, 0x2000
	s_add_u32 s20, s36, 0x40000
	v_lshl_add_u64 v[216:217], s[36:37], 0, v[130:131]
	s_addc_u32 s21, s37, 0
	s_add_i32 s77, s78, s47
	global_load_lds_dwordx4 v[216:217], off
	ds_read_b128 v[178:181], v148 offset:16384
	ds_read_b128 v[182:185], v148 offset:17408
	ds_read_b128 v[186:189], v148 offset:18432
	ds_read_b128 v[190:193], v148 offset:19456
	ds_read_b128 v[194:197], v148 offset:20480
	ds_read_b128 v[198:201], v148 offset:21504
	ds_read_b128 v[208:211], v148 offset:22528
	ds_read_b128 v[212:215], v148 offset:23552
	v_lshl_add_u64 v[218:219], s[20:21], 0, v[0:1]
	s_mov_b32 m0, s77
	v_lshl_add_u64 v[220:221], s[38:39], 0, v[132:133]
	global_load_lds_dwordx4 v[218:219], off
	v_lshl_add_u64 v[218:219], s[20:21], 0, v[130:131]
	s_add_i32 m0, s77, 0x2000
	s_nop 0
	global_load_lds_dwordx4 v[218:219], off
	v_lshl_add_u64 v[218:219], s[38:39], 0, v[134:135]
	s_mov_b32 m0, s52
	s_nop 0
	global_load_lds_dwordx4 v[218:219], off
	s_mov_b32 m0, s53
	s_nop 0
	global_load_lds_dwordx4 v[220:221], off
	s_waitcnt vmcnt(8)
	s_waitcnt lgkmcnt(0)
	s_barrier
; #define PG8_STAGE(bufoff, gbase, voff) do { _Pragma("unroll") for (int _i = 0; _i < 2; ++_i) \
;         __builtin_amdgcn_global_load_lds((const unsigned*)((const char*)(gbase) + (voff)[_i]), (PG8_LAS unsigned*)(lds + (bufoff) + ldsw + _i * 8192), 16, 0, 0); } while (0)
; #define PG8_LDA(dst, b, h) do { _Pragma("unroll") for (int m = 0; m < 4; ++m) _Pragma("unroll") for (int k = 0; k < 2; ++k) dst[m][k] = *(const PG8_LAS bf16x8*)(lds + PG8_SA(b, h) + aoff + m * 2048 + k * 1024); } while (0)
; #define PG8_LDB(dst, b, h) do { _Pragma("unroll") for (int n = 0; n < 2; ++n) _Pragma("unroll") for (int k = 0; k < 2; ++k) dst[n][k] = *(const PG8_LAS bf16x8*)(lds + PG8_SB(b, h) + boff + n * 2048 + k * 1024); } while (0)
; #define PG8_MMA(ai, bj, At, Bt) do { __builtin_amdgcn_s_setprio(1); _Pragma("unroll") for (int m = 0; m < 4; ++m) _Pragma("unroll") for (int n = 0; n < 2; ++n) _Pragma("unroll") for (int k = 0; k < 2; ++k) \
;         acc[ai][bj][m][n] = __builtin_amdgcn_mfma_f32_16x16x32_bf16(Bt[n][k], At[m][k], acc[ai][bj][m][n], 0, 0, 0); __builtin_amdgcn_s_setprio(0); } while (0)
; #define PG8_WAIT_V(n) asm volatile("s_waitcnt vmcnt(" #n ")" ::: "memory")
; #define PG8_WAIT_L(n) asm volatile("s_waitcnt lgkmcnt(" #n ")" ::: "memory")
; #define PG8_BAR __builtin_amdgcn_s_barrier()
; #define PG8_SCHED __builtin_amdgcn_sched_barrier(0)
; template <class Epi, class Sched, bool ALIGN_EPI = false, bool SP2 = false>
; __device__ __forceinline__ void gemm_phase(PG8_LAS unsigned char* lds, const Gemm g, const Sched& S, const Epi& E) {
;     ...
;             PG8_WAIT_V(8); PG8_WAIT_L(0); PG8_BAR; PG8_MMA(1, 0, At, B0); PG8_MMA(1, 1, At, B1); PG8_BAR; PG8_SCHED;
;             PG8_LDB(B0, 1, 0); PG8_LDB(B1, 1, 1); PG8_SCHED; PG8_LDA(At, 1, 0); PG8_STAGE(PG8_SA(0, 1), a2 + hstepA, voffA);
;             PG8_WAIT_V(8); PG8_WAIT_L(0); PG8_BAR; PG8_MMA(0, 0, At, B0); PG8_MMA(0, 1, At, B1); PG8_BAR; PG8_SCHED;
	s_setprio 1
	s_waitcnt lgkmcnt(0)
	v_mfma_f32_16x16x32_bf16 v[62:65], v[140:143], v[178:181], 0
	v_mfma_f32_16x16x32_bf16 v[54:57], v[154:157], v[178:181], 0
	v_mfma_f32_16x16x32_bf16 v[46:49], v[140:143], v[186:189], 0
	v_mfma_f32_16x16x32_bf16 v[38:41], v[154:157], v[186:189], 0
	v_mfma_f32_16x16x32_bf16 v[30:33], v[140:143], v[194:197], 0
	v_mfma_f32_16x16x32_bf16 v[22:25], v[154:157], v[194:197], 0
	v_mfma_f32_16x16x32_bf16 v[14:17], v[140:143], v[208:211], 0
	v_mfma_f32_16x16x32_bf16 v[6:9], v[154:157], v[208:211], 0
	v_mfma_f32_16x16x32_bf16 v[62:65], v[150:153], v[182:185], v[62:65]
	v_mfma_f32_16x16x32_bf16 v[54:57], v[158:161], v[182:185], v[54:57]
	v_mfma_f32_16x16x32_bf16 v[46:49], v[150:153], v[190:193], v[46:49]
	v_mfma_f32_16x16x32_bf16 v[38:41], v[158:161], v[190:193], v[38:41]
	v_mfma_f32_16x16x32_bf16 v[30:33], v[150:153], v[198:201], v[30:33]
	v_mfma_f32_16x16x32_bf16 v[22:25], v[158:161], v[198:201], v[22:25]
	v_mfma_f32_16x16x32_bf16 v[14:17], v[150:153], v[212:215], v[14:17]
	v_mfma_f32_16x16x32_bf16 v[6:9], v[158:161], v[212:215], v[6:9]
	s_setprio 0
	s_setprio 1
	v_mfma_f32_16x16x32_bf16 v[58:61], v[162:165], v[178:181], 0
	v_mfma_f32_16x16x32_bf16 v[50:53], v[170:173], v[178:181], 0
	v_mfma_f32_16x16x32_bf16 v[42:45], v[162:165], v[186:189], 0
	v_mfma_f32_16x16x32_bf16 v[34:37], v[170:173], v[186:189], 0
	v_mfma_f32_16x16x32_bf16 v[26:29], v[162:165], v[194:197], 0
	v_mfma_f32_16x16x32_bf16 v[18:21], v[170:173], v[194:197], 0
	v_mfma_f32_16x16x32_bf16 v[10:13], v[162:165], v[208:211], 0
	v_mfma_f32_16x16x32_bf16 v[2:5], v[170:173], v[208:211], 0
	v_mfma_f32_16x16x32_bf16 v[58:61], v[166:169], v[182:185], v[58:61]
	v_mfma_f32_16x16x32_bf16 v[50:53], v[174:177], v[182:185], v[50:53]
	v_mfma_f32_16x16x32_bf16 v[42:45], v[166:169], v[190:193], v[42:45]
	v_mfma_f32_16x16x32_bf16 v[34:37], v[174:177], v[190:193], v[34:37]
	v_mfma_f32_16x16x32_bf16 v[26:29], v[166:169], v[198:201], v[26:29]
	v_mfma_f32_16x16x32_bf16 v[18:21], v[174:177], v[198:201], v[18:21]
	v_mfma_f32_16x16x32_bf16 v[10:13], v[166:169], v[212:215], v[10:13]
	v_mfma_f32_16x16x32_bf16 v[2:5], v[174:177], v[212:215], v[2:5]
	s_setprio 0
	s_barrier
	s_add_i32 s77, 0, 0x18000
	s_add_i32 s78, 0, 0x1c000
	s_add_u32 s20, s38, 0x40000
	s_addc_u32 s21, s39, 0
	s_mov_b32 m0, s54
	v_lshl_add_u64 v[222:223], s[20:21], 0, v[134:135]
	global_load_lds_dwordx4 v[222:223], off
	v_lshl_add_u64 v[222:223], s[20:21], 0, v[132:133]
	s_mov_b32 m0, s55
	s_nop 0
	global_load_lds_dwordx4 v[222:223], off
	v_add_u32_e32 v149, s77, v146
	ds_read_b128 v[140:143], v149
	ds_read_b128 v[150:153], v149 offset:1024
	ds_read_b128 v[154:157], v149 offset:2048
	ds_read_b128 v[158:161], v149 offset:3072
	v_add_u32_e32 v149, s78, v146
	ds_read_b128 v[162:165], v149
	ds_read_b128 v[166:169], v149 offset:1024
	ds_read_b128 v[170:173], v149 offset:2048
	ds_read_b128 v[174:177], v149 offset:3072
	ds_read_b128 v[178:181], v148 offset:32768
	ds_read_b128 v[182:185], v148 offset:33792
	ds_read_b128 v[186:189], v148 offset:34816
	ds_read_b128 v[190:193], v148 offset:35840
	ds_read_b128 v[194:197], v148 offset:36864
	ds_read_b128 v[198:201], v148 offset:37888
	ds_read_b128 v[208:211], v148 offset:38912
	ds_read_b128 v[212:215], v148 offset:39936
	s_waitcnt vmcnt(8)
	s_waitcnt lgkmcnt(0)
	s_barrier
	s_setprio 1
	s_waitcnt lgkmcnt(0)
	v_mfma_f32_16x16x32_bf16 v[126:129], v[140:143], v[178:181], v[126:129]
	v_mfma_f32_16x16x32_bf16 v[118:121], v[154:157], v[178:181], v[118:121]
	v_mfma_f32_16x16x32_bf16 v[110:113], v[140:143], v[186:189], v[110:113]
	v_mfma_f32_16x16x32_bf16 v[102:105], v[154:157], v[186:189], v[102:105]
	v_mfma_f32_16x16x32_bf16 v[94:97], v[140:143], v[194:197], v[94:97]
	v_mfma_f32_16x16x32_bf16 v[86:89], v[154:157], v[194:197], v[86:89]
	v_mfma_f32_16x16x32_bf16 v[78:81], v[140:143], v[208:211], v[78:81]
	v_mfma_f32_16x16x32_bf16 v[70:73], v[154:157], v[208:211], v[70:73]
	v_mfma_f32_16x16x32_bf16 v[126:129], v[150:153], v[182:185], v[126:129]
	v_mfma_f32_16x16x32_bf16 v[118:121], v[158:161], v[182:185], v[118:121]
	v_mfma_f32_16x16x32_bf16 v[110:113], v[150:153], v[190:193], v[110:113]
	v_mfma_f32_16x16x32_bf16 v[102:105], v[158:161], v[190:193], v[102:105]
	v_mfma_f32_16x16x32_bf16 v[94:97], v[150:153], v[198:201], v[94:97]
	v_mfma_f32_16x16x32_bf16 v[86:89], v[158:161], v[198:201], v[86:89]
	v_mfma_f32_16x16x32_bf16 v[78:81], v[150:153], v[212:215], v[78:81]
	v_mfma_f32_16x16x32_bf16 v[70:73], v[158:161], v[212:215], v[70:73]
	s_setprio 0
	s_setprio 1
	v_mfma_f32_16x16x32_bf16 v[122:125], v[162:165], v[178:181], v[122:125]
	v_mfma_f32_16x16x32_bf16 v[114:117], v[170:173], v[178:181], v[114:117]
	v_mfma_f32_16x16x32_bf16 v[106:109], v[162:165], v[186:189], v[106:109]
	v_mfma_f32_16x16x32_bf16 v[98:101], v[170:173], v[186:189], v[98:101]
	v_mfma_f32_16x16x32_bf16 v[90:93], v[162:165], v[194:197], v[90:93]
	v_mfma_f32_16x16x32_bf16 v[82:85], v[170:173], v[194:197], v[82:85]
	v_mfma_f32_16x16x32_bf16 v[74:77], v[162:165], v[208:211], v[74:77]
	v_mfma_f32_16x16x32_bf16 v[66:69], v[170:173], v[208:211], v[66:69]
	v_mfma_f32_16x16x32_bf16 v[122:125], v[166:169], v[182:185], v[122:125]
	v_mfma_f32_16x16x32_bf16 v[114:117], v[174:177], v[182:185], v[114:117]
	v_mfma_f32_16x16x32_bf16 v[106:109], v[166:169], v[190:193], v[106:109]
	v_mfma_f32_16x16x32_bf16 v[98:101], v[174:177], v[190:193], v[98:101]
	v_mfma_f32_16x16x32_bf16 v[90:93], v[166:169], v[198:201], v[90:93]
	v_mfma_f32_16x16x32_bf16 v[82:85], v[174:177], v[198:201], v[82:85]
	v_mfma_f32_16x16x32_bf16 v[74:77], v[166:169], v[212:215], v[74:77]
	v_mfma_f32_16x16x32_bf16 v[66:69], v[174:177], v[212:215], v[66:69]
	s_setprio 0
	s_barrier
; #define PG8_STAGE(bufoff, gbase, voff) do { _Pragma("unroll") for (int _i = 0; _i < 2; ++_i) \
;         __builtin_amdgcn_global_load_lds((const unsigned*)((const char*)(gbase) + (voff)[_i]), (PG8_LAS unsigned*)(lds + (bufoff) + ldsw + _i * 8192), 16, 0, 0); } while (0)
; #define PG8_LDA(dst, b, h) do { _Pragma("unroll") for (int m = 0; m < 4; ++m) _Pragma("unroll") for (int k = 0; k < 2; ++k) dst[m][k] = *(const PG8_LAS bf16x8*)(lds + PG8_SA(b, h) + aoff + m * 2048 + k * 1024); } while (0)
; #define PG8_LDB(dst, b, h) do { _Pragma("unroll") for (int n = 0; n < 2; ++n) _Pragma("unroll") for (int k = 0; k < 2; ++k) dst[n][k] = *(const PG8_LAS bf16x8*)(lds + PG8_SB(b, h) + boff + n * 2048 + k * 1024); } while (0)
; #define PG8_MMA(ai, bj, At, Bt) do { __builtin_amdgcn_s_setprio(1); _Pragma("unroll") for (int m = 0; m < 4; ++m) _Pragma("unroll") for (int n = 0; n < 2; ++n) _Pragma("unroll") for (int k = 0; k < 2; ++k) \
;         acc[ai][bj][m][n] = __builtin_amdgcn_mfma_f32_16x16x32_bf16(Bt[n][k], At[m][k], acc[ai][bj][m][n], 0, 0, 0); __builtin_amdgcn_s_setprio(0); } while (0)
; #define PG8_WAIT_V(n) asm volatile("s_waitcnt vmcnt(" #n ")" ::: "memory")
; #define PG8_WAIT_L(n) asm volatile("s_waitcnt lgkmcnt(" #n ")" ::: "memory")
; #define PG8_BAR __builtin_amdgcn_s_barrier()
; #define PG8_SCHED __builtin_amdgcn_sched_barrier(0)
; template <class Epi, class Sched, bool ALIGN_EPI = false, bool SP2 = false>
; __device__ __forceinline__ void gemm_phase(PG8_LAS unsigned char* lds, const Gemm g, const Sched& S, const Epi& E) {
;     ...
;             PG8_LDB(B0, 0, 0); PG8_LDB(B1, 0, 1); PG8_SCHED; PG8_LDA(At, 0, 0); PG8_STAGE(PG8_SA(1, 1), a1 + hstepA, voffA);
;             PG8_WAIT_V(8); PG8_WAIT_L(0); PG8_BAR; PG8_MMA(0, 0, At, B0); PG8_MMA(0, 1, At, B1); PG8_BAR; PG8_SCHED;
;     ...
;             PG8_LDA(At, 1, 1); PG8_STAGE(PG8_SB(1, 0), b3, voffB); PG8_STAGE(PG8_SB(1, 1), b3 + hstepB, voffB); PG8_STAGE(PG8_SA(1, 0), a3, voffA);
;             PG8_WAIT_V(8); PG8_WAIT_L(0); PG8_BAR; PG8_MMA(1, 0, At, B0); PG8_MMA(1, 1, At, B1); PG8_BAR; PG8_SCHED;
	s_add_i32 s20, s77, s47
	v_lshl_add_u64 v[204:205], v[204:205], 0, s[22:23]
	s_mov_b32 m0, s20
	s_nop 0
	global_load_lds_dwordx4 v[204:205], off
	s_add_i32 m0, s20, 0x2000
	s_add_u32 s20, s36, 0x40080
	v_lshl_add_u64 v[204:205], v[216:217], 0, s[22:23]
	s_addc_u32 s21, s37, 0
	s_add_i32 s36, s78, s47
	global_load_lds_dwordx4 v[204:205], off
	ds_read_b128 v[178:181], v148 offset:49152
	ds_read_b128 v[182:185], v148 offset:50176
	ds_read_b128 v[186:189], v148 offset:51200
	ds_read_b128 v[190:193], v148 offset:52224
	ds_read_b128 v[194:197], v148 offset:53248
	ds_read_b128 v[198:201], v148 offset:54272
	ds_read_b128 v[208:211], v148 offset:55296
	ds_read_b128 v[212:215], v148 offset:56320
	v_lshl_add_u64 v[204:205], s[20:21], 0, v[0:1]
	s_mov_b32 m0, s36
	s_nop 0
	global_load_lds_dwordx4 v[204:205], off
	v_lshl_add_u64 v[204:205], s[20:21], 0, v[130:131]
	s_add_i32 m0, s36, 0x2000
	s_nop 0
	global_load_lds_dwordx4 v[204:205], off
	v_lshl_add_u64 v[204:205], v[218:219], 0, s[22:23]
	s_mov_b32 m0, s56
	s_nop 0
	global_load_lds_dwordx4 v[204:205], off
	v_lshl_add_u64 v[204:205], v[220:221], 0, s[22:23]
	s_mov_b32 m0, s57
	s_nop 0
	global_load_lds_dwordx4 v[204:205], off
	s_waitcnt vmcnt(8)
	s_waitcnt lgkmcnt(0)
	s_barrier
	s_setprio 1
	s_waitcnt lgkmcnt(0)
	v_mfma_f32_16x16x32_bf16 v[62:65], v[140:143], v[178:181], v[62:65]
	v_mfma_f32_16x16x32_bf16 v[54:57], v[154:157], v[178:181], v[54:57]
	v_mfma_f32_16x16x32_bf16 v[46:49], v[140:143], v[186:189], v[46:49]
	v_mfma_f32_16x16x32_bf16 v[38:41], v[154:157], v[186:189], v[38:41]
	v_mfma_f32_16x16x32_bf16 v[30:33], v[140:143], v[194:197], v[30:33]
	v_mfma_f32_16x16x32_bf16 v[22:25], v[154:157], v[194:197], v[22:25]
	v_mfma_f32_16x16x32_bf16 v[14:17], v[140:143], v[208:211], v[14:17]
	v_mfma_f32_16x16x32_bf16 v[6:9], v[154:157], v[208:211], v[6:9]
	v_mfma_f32_16x16x32_bf16 v[62:65], v[150:153], v[182:185], v[62:65]
	v_mfma_f32_16x16x32_bf16 v[54:57], v[158:161], v[182:185], v[54:57]
	v_mfma_f32_16x16x32_bf16 v[46:49], v[150:153], v[190:193], v[46:49]
	v_mfma_f32_16x16x32_bf16 v[38:41], v[158:161], v[190:193], v[38:41]
	v_mfma_f32_16x16x32_bf16 v[30:33], v[150:153], v[198:201], v[30:33]
	v_mfma_f32_16x16x32_bf16 v[22:25], v[158:161], v[198:201], v[22:25]
	v_mfma_f32_16x16x32_bf16 v[14:17], v[150:153], v[212:215], v[14:17]
	v_mfma_f32_16x16x32_bf16 v[6:9], v[158:161], v[212:215], v[6:9]
	s_setprio 0
	s_setprio 1
	v_mfma_f32_16x16x32_bf16 v[58:61], v[162:165], v[178:181], v[58:61]
	v_mfma_f32_16x16x32_bf16 v[50:53], v[170:173], v[178:181], v[50:53]
	v_mfma_f32_16x16x32_bf16 v[42:45], v[162:165], v[186:189], v[42:45]
	v_mfma_f32_16x16x32_bf16 v[34:37], v[170:173], v[186:189], v[34:37]
	v_mfma_f32_16x16x32_bf16 v[26:29], v[162:165], v[194:197], v[26:29]
	v_mfma_f32_16x16x32_bf16 v[18:21], v[170:173], v[194:197], v[18:21]
	v_mfma_f32_16x16x32_bf16 v[10:13], v[162:165], v[208:211], v[10:13]
	v_mfma_f32_16x16x32_bf16 v[2:5], v[170:173], v[208:211], v[2:5]
	v_mfma_f32_16x16x32_bf16 v[58:61], v[166:169], v[182:185], v[58:61]
	v_mfma_f32_16x16x32_bf16 v[50:53], v[174:177], v[182:185], v[50:53]
	v_mfma_f32_16x16x32_bf16 v[42:45], v[166:169], v[190:193], v[42:45]
	v_mfma_f32_16x16x32_bf16 v[34:37], v[174:177], v[190:193], v[34:37]
	v_mfma_f32_16x16x32_bf16 v[26:29], v[166:169], v[198:201], v[26:29]
	v_mfma_f32_16x16x32_bf16 v[18:21], v[174:177], v[198:201], v[18:21]
	v_mfma_f32_16x16x32_bf16 v[10:13], v[166:169], v[212:215], v[10:13]
	v_mfma_f32_16x16x32_bf16 v[2:5], v[174:177], v[212:215], v[2:5]
	s_setprio 0
	s_barrier
	s_add_i32 s76, s76, 2
	s_add_u32 s8, s8, 0x100
	s_addc_u32 s9, s9, 0
	s_add_u32 s70, s70, 0x100
	s_addc_u32 s71, s71, 0
	s_cmp_gt_u32 s76, 13
	s_cbranch_scc1 .Lpk_done_up
.LBB0_1212:
	s_add_u32 s20, s8, 0xfffc0080
	s_addc_u32 s21, s9, -1
	s_add_i32 s77, 0, 0x10000
	s_cmp_eq_u32 s76, 12
	s_cselect_b32 s39, s29, s21
	s_cselect_b32 s38, s62, s20
	s_cselect_b32 s37, s19, s71
	s_cselect_b32 s36, s63, s70
	s_add_i32 s78, 0, 0x14000
	v_lshl_add_u64 v[204:205], s[8:9], 0, v[136:137]
	s_add_i32 m0, s52, 0xc000
	s_nop 0
	global_load_lds_dwordx4 v[204:205], off
	v_lshl_add_u64 v[204:205], s[8:9], 0, v[138:139]
	s_add_i32 m0, s52, 0xe000
	s_nop 0
	global_load_lds_dwordx4 v[204:205], off
	v_add_u32_e32 v149, s77, v146
	ds_read_b128 v[140:143], v149
	ds_read_b128 v[150:153], v149 offset:1024
	ds_read_b128 v[154:157], v149 offset:2048
	ds_read_b128 v[158:161], v149 offset:3072
	v_add_u32_e32 v149, s78, v146
	ds_read_b128 v[162:165], v149
	ds_read_b128 v[166:169], v149 offset:1024
	ds_read_b128 v[170:173], v149 offset:2048
	ds_read_b128 v[174:177], v149 offset:3072
	ds_read_b128 v[178:181], v148
	ds_read_b128 v[182:185], v148 offset:1024
	ds_read_b128 v[186:189], v148 offset:2048
	ds_read_b128 v[190:193], v148 offset:3072
	ds_read_b128 v[194:197], v148 offset:4096
	ds_read_b128 v[198:201], v148 offset:5120
	ds_read_b128 v[208:211], v148 offset:6144
	ds_read_b128 v[212:215], v148 offset:7168
	s_waitcnt vmcnt(8)
	s_waitcnt lgkmcnt(0)
	s_barrier
; #define PG8_STAGE(bufoff, gbase, voff) do { _Pragma("unroll") for (int _i = 0; _i < 2; ++_i) \
;         __builtin_amdgcn_global_load_lds((const unsigned*)((const char*)(gbase) + (voff)[_i]), (PG8_LAS unsigned*)(lds + (bufoff) + ldsw + _i * 8192), 16, 0, 0); } while (0)
; #define PG8_LDA(dst, b, h) do { _Pragma("unroll") for (int m = 0; m < 4; ++m) _Pragma("unroll") for (int k = 0; k < 2; ++k) dst[m][k] = *(const PG8_LAS bf16x8*)(lds + PG8_SA(b, h) + aoff + m * 2048 + k * 1024); } while (0)
; #define PG8_MMA(ai, bj, At, Bt) do { __builtin_amdgcn_s_setprio(1); _Pragma("unroll") for (int m = 0; m < 4; ++m) _Pragma("unroll") for (int n = 0; n < 2; ++n) _Pragma("unroll") for (int k = 0; k < 2; ++k) \
;         acc[ai][bj][m][n] = __builtin_amdgcn_mfma_f32_16x16x32_bf16(Bt[n][k], At[m][k], acc[ai][bj][m][n], 0, 0, 0); __builtin_amdgcn_s_setprio(0); } while (0)
; #define PG8_WAIT_V(n) asm volatile("s_waitcnt vmcnt(" #n ")" ::: "memory")
; #define PG8_WAIT_L(n) asm volatile("s_waitcnt lgkmcnt(" #n ")" ::: "memory")
; #define PG8_BAR __builtin_amdgcn_s_barrier()
; #define PG8_SCHED __builtin_amdgcn_sched_barrier(0)
; template <class Epi, class Sched, bool ALIGN_EPI = false, bool SP2 = false>
; __device__ __forceinline__ void gemm_phase(PG8_LAS unsigned char* lds, const Gemm g, const Sched& S, const Epi& E) {
;     ...
;             PG8_WAIT_V(8); PG8_WAIT_L(0); PG8_BAR; PG8_MMA(0, 0, At, B0); PG8_MMA(0, 1, At, B1); PG8_BAR; PG8_SCHED;
;             PG8_LDA(At, 0, 1); PG8_STAGE(PG8_SB(0, 0), b2, voffB); PG8_STAGE(PG8_SB(0, 1), b2 + hstepB, voffB); PG8_STAGE(PG8_SA(0, 0), a2, voffA);
;             PG8_WAIT_V(8); PG8_WAIT_L(0); PG8_BAR; PG8_MMA(1, 0, At, B0); PG8_MMA(1, 1, At, B1); PG8_BAR; PG8_SCHED;
	s_setprio 1
	s_waitcnt lgkmcnt(0)
	v_mfma_f32_16x16x32_bf16 v[126:129], v[140:143], v[178:181], v[126:129]
	v_mfma_f32_16x16x32_bf16 v[118:121], v[154:157], v[178:181], v[118:121]
	v_mfma_f32_16x16x32_bf16 v[110:113], v[140:143], v[186:189], v[110:113]
	v_mfma_f32_16x16x32_bf16 v[102:105], v[154:157], v[186:189], v[102:105]
	v_mfma_f32_16x16x32_bf16 v[94:97], v[140:143], v[194:197], v[94:97]
	v_mfma_f32_16x16x32_bf16 v[86:89], v[154:157], v[194:197], v[86:89]
	v_mfma_f32_16x16x32_bf16 v[78:81], v[140:143], v[208:211], v[78:81]
	v_mfma_f32_16x16x32_bf16 v[70:73], v[154:157], v[208:211], v[70:73]
	v_mfma_f32_16x16x32_bf16 v[126:129], v[150:153], v[182:185], v[126:129]
	v_mfma_f32_16x16x32_bf16 v[118:121], v[158:161], v[182:185], v[118:121]
	v_mfma_f32_16x16x32_bf16 v[110:113], v[150:153], v[190:193], v[110:113]
	v_mfma_f32_16x16x32_bf16 v[102:105], v[158:161], v[190:193], v[102:105]
	v_mfma_f32_16x16x32_bf16 v[94:97], v[150:153], v[198:201], v[94:97]
	v_mfma_f32_16x16x32_bf16 v[86:89], v[158:161], v[198:201], v[86:89]
	v_mfma_f32_16x16x32_bf16 v[78:81], v[150:153], v[212:215], v[78:81]
	v_mfma_f32_16x16x32_bf16 v[70:73], v[158:161], v[212:215], v[70:73]
	s_setprio 0
	s_setprio 1
	v_mfma_f32_16x16x32_bf16 v[122:125], v[162:165], v[178:181], v[122:125]
	v_mfma_f32_16x16x32_bf16 v[114:117], v[170:173], v[178:181], v[114:117]
	v_mfma_f32_16x16x32_bf16 v[106:109], v[162:165], v[186:189], v[106:109]
	v_mfma_f32_16x16x32_bf16 v[98:101], v[170:173], v[186:189], v[98:101]
	v_mfma_f32_16x16x32_bf16 v[90:93], v[162:165], v[194:197], v[90:93]
	v_mfma_f32_16x16x32_bf16 v[82:85], v[170:173], v[194:197], v[82:85]
	v_mfma_f32_16x16x32_bf16 v[74:77], v[162:165], v[208:211], v[74:77]
	v_mfma_f32_16x16x32_bf16 v[66:69], v[170:173], v[208:211], v[66:69]
	v_mfma_f32_16x16x32_bf16 v[122:125], v[166:169], v[182:185], v[122:125]
	v_mfma_f32_16x16x32_bf16 v[114:117], v[174:177], v[182:185], v[114:117]
	v_mfma_f32_16x16x32_bf16 v[106:109], v[166:169], v[190:193], v[106:109]
	v_mfma_f32_16x16x32_bf16 v[98:101], v[174:177], v[190:193], v[98:101]
	v_mfma_f32_16x16x32_bf16 v[90:93], v[166:169], v[198:201], v[90:93]
	v_mfma_f32_16x16x32_bf16 v[82:85], v[174:177], v[198:201], v[82:85]
	v_mfma_f32_16x16x32_bf16 v[74:77], v[166:169], v[212:215], v[74:77]
	v_mfma_f32_16x16x32_bf16 v[66:69], v[174:177], v[212:215], v[66:69]
	s_setprio 0
	s_barrier
	s_add_i32 s20, s77, s47
	v_lshl_add_u64 v[204:205], s[36:37], 0, v[0:1]
	s_mov_b32 m0, s20
	s_nop 0
	global_load_lds_dwordx4 v[204:205], off
	s_add_i32 m0, s20, 0x2000
	s_add_u32 s20, s36, 0x40000
	v_lshl_add_u64 v[216:217], s[36:37], 0, v[130:131]
	s_addc_u32 s21, s37, 0
	s_add_i32 s77, s78, s47
	global_load_lds_dwordx4 v[216:217], off
	ds_read_b128 v[178:181], v148 offset:16384
	ds_read_b128 v[182:185], v148 offset:17408
	ds_read_b128 v[186:189], v148 offset:18432
	ds_read_b128 v[190:193], v148 offset:19456
	ds_read_b128 v[194:197], v148 offset:20480
	ds_read_b128 v[198:201], v148 offset:21504
	ds_read_b128 v[208:211], v148 offset:22528
	ds_read_b128 v[212:215], v148 offset:23552
	v_lshl_add_u64 v[218:219], s[20:21], 0, v[0:1]
	s_mov_b32 m0, s77
	v_lshl_add_u64 v[220:221], s[38:39], 0, v[132:133]
	global_load_lds_dwordx4 v[218:219], off
	v_lshl_add_u64 v[218:219], s[20:21], 0, v[130:131]
	s_add_i32 m0, s77, 0x2000
	s_nop 0
	global_load_lds_dwordx4 v[218:219], off
	v_lshl_add_u64 v[218:219], s[38:39], 0, v[134:135]
	s_mov_b32 m0, s52
	s_nop 0
	global_load_lds_dwordx4 v[218:219], off
	s_mov_b32 m0, s53
	s_nop 0
	global_load_lds_dwordx4 v[220:221], off
	s_waitcnt vmcnt(8)
	s_waitcnt lgkmcnt(0)
	s_barrier
	s_setprio 1
	s_waitcnt lgkmcnt(0)
	v_mfma_f32_16x16x32_bf16 v[62:65], v[140:143], v[178:181], v[62:65]
	v_mfma_f32_16x16x32_bf16 v[54:57], v[154:157], v[178:181], v[54:57]
	v_mfma_f32_16x16x32_bf16 v[46:49], v[140:143], v[186:189], v[46:49]
	v_mfma_f32_16x16x32_bf16 v[38:41], v[154:157], v[186:189], v[38:41]
	v_mfma_f32_16x16x32_bf16 v[30:33], v[140:143], v[194:197], v[30:33]
	v_mfma_f32_16x16x32_bf16 v[22:25], v[154:157], v[194:197], v[22:25]
	v_mfma_f32_16x16x32_bf16 v[14:17], v[140:143], v[208:211], v[14:17]
	v_mfma_f32_16x16x32_bf16 v[6:9], v[154:157], v[208:211], v[6:9]
	v_mfma_f32_16x16x32_bf16 v[62:65], v[150:153], v[182:185], v[62:65]
	v_mfma_f32_16x16x32_bf16 v[54:57], v[158:161], v[182:185], v[54:57]
	v_mfma_f32_16x16x32_bf16 v[46:49], v[150:153], v[190:193], v[46:49]
	v_mfma_f32_16x16x32_bf16 v[38:41], v[158:161], v[190:193], v[38:41]
	v_mfma_f32_16x16x32_bf16 v[30:33], v[150:153], v[198:201], v[30:33]
	v_mfma_f32_16x16x32_bf16 v[22:25], v[158:161], v[198:201], v[22:25]
	v_mfma_f32_16x16x32_bf16 v[14:17], v[150:153], v[212:215], v[14:17]
	v_mfma_f32_16x16x32_bf16 v[6:9], v[158:161], v[212:215], v[6:9]
	s_setprio 0
	s_setprio 1
	v_mfma_f32_16x16x32_bf16 v[58:61], v[162:165], v[178:181], v[58:61]
	v_mfma_f32_16x16x32_bf16 v[50:53], v[170:173], v[178:181], v[50:53]
	v_mfma_f32_16x16x32_bf16 v[42:45], v[162:165], v[186:189], v[42:45]
	v_mfma_f32_16x16x32_bf16 v[34:37], v[170:173], v[186:189], v[34:37]
	v_mfma_f32_16x16x32_bf16 v[26:29], v[162:165], v[194:197], v[26:29]
	v_mfma_f32_16x16x32_bf16 v[18:21], v[170:173], v[194:197], v[18:21]
	v_mfma_f32_16x16x32_bf16 v[10:13], v[162:165], v[208:211], v[10:13]
	v_mfma_f32_16x16x32_bf16 v[2:5], v[170:173], v[208:211], v[2:5]
	v_mfma_f32_16x16x32_bf16 v[58:61], v[166:169], v[182:185], v[58:61]
	v_mfma_f32_16x16x32_bf16 v[50:53], v[174:177], v[182:185], v[50:53]
	v_mfma_f32_16x16x32_bf16 v[42:45], v[166:169], v[190:193], v[42:45]
	v_mfma_f32_16x16x32_bf16 v[34:37], v[174:177], v[190:193], v[34:37]
	v_mfma_f32_16x16x32_bf16 v[26:29], v[166:169], v[198:201], v[26:29]
	v_mfma_f32_16x16x32_bf16 v[18:21], v[174:177], v[198:201], v[18:21]
	v_mfma_f32_16x16x32_bf16 v[10:13], v[166:169], v[212:215], v[10:13]
	v_mfma_f32_16x16x32_bf16 v[2:5], v[174:177], v[212:215], v[2:5]
	s_setprio 0
	s_barrier
; #define PG8_STAGE(bufoff, gbase, voff) do { _Pragma("unroll") for (int _i = 0; _i < 2; ++_i) \
;         __builtin_amdgcn_global_load_lds((const unsigned*)((const char*)(gbase) + (voff)[_i]), (PG8_LAS unsigned*)(lds + (bufoff) + ldsw + _i * 8192), 16, 0, 0); } while (0)
; #define PG8_LDA(dst, b, h) do { _Pragma("unroll") for (int m = 0; m < 4; ++m) _Pragma("unroll") for (int k = 0; k < 2; ++k) dst[m][k] = *(const PG8_LAS bf16x8*)(lds + PG8_SA(b, h) + aoff + m * 2048 + k * 1024); } while (0)
; #define PG8_LDB(dst, b, h) do { _Pragma("unroll") for (int n = 0; n < 2; ++n) _Pragma("unroll") for (int k = 0; k < 2; ++k) dst[n][k] = *(const PG8_LAS bf16x8*)(lds + PG8_SB(b, h) + boff + n * 2048 + k * 1024); } while (0)
; #define PG8_MMA(ai, bj, At, Bt) do { __builtin_amdgcn_s_setprio(1); _Pragma("unroll") for (int m = 0; m < 4; ++m) _Pragma("unroll") for (int n = 0; n < 2; ++n) _Pragma("unroll") for (int k = 0; k < 2; ++k) \
;         acc[ai][bj][m][n] = __builtin_amdgcn_mfma_f32_16x16x32_bf16(Bt[n][k], At[m][k], acc[ai][bj][m][n], 0, 0, 0); __builtin_amdgcn_s_setprio(0); } while (0)
; #define PG8_WAIT_V(n) asm volatile("s_waitcnt vmcnt(" #n ")" ::: "memory")
; #define PG8_WAIT_L(n) asm volatile("s_waitcnt lgkmcnt(" #n ")" ::: "memory")
; #define PG8_BAR __builtin_amdgcn_s_barrier()
; #define PG8_SCHED __builtin_amdgcn_sched_barrier(0)
; template <class Epi, class Sched, bool ALIGN_EPI = false, bool SP2 = false>
; __device__ __forceinline__ void gemm_phase(PG8_LAS unsigned char* lds, const Gemm g, const Sched& S, const Epi& E) {
;     ...
;             PG8_LDB(B0, 1, 0); PG8_LDB(B1, 1, 1); PG8_SCHED; PG8_LDA(At, 1, 0); PG8_STAGE(PG8_SA(0, 1), a2 + hstepA, voffA);
;             PG8_WAIT_V(8); PG8_WAIT_L(0); PG8_BAR; PG8_MMA(0, 0, At, B0); PG8_MMA(0, 1, At, B1); PG8_BAR; PG8_SCHED;
	s_add_i32 s77, 0, 0x18000
	s_add_i32 s78, 0, 0x1c000
	s_add_u32 s20, s38, 0x40000
	s_addc_u32 s21, s39, 0
	s_mov_b32 m0, s54
	v_lshl_add_u64 v[222:223], s[20:21], 0, v[134:135]
	global_load_lds_dwordx4 v[222:223], off
	v_lshl_add_u64 v[222:223], s[20:21], 0, v[132:133]
	s_mov_b32 m0, s55
	s_nop 0
	global_load_lds_dwordx4 v[222:223], off
	v_add_u32_e32 v149, s77, v146
	ds_read_b128 v[140:143], v149
	ds_read_b128 v[150:153], v149 offset:1024
	ds_read_b128 v[154:157], v149 offset:2048
	ds_read_b128 v[158:161], v149 offset:3072
	v_add_u32_e32 v149, s78, v146
	ds_read_b128 v[162:165], v149
	ds_read_b128 v[166:169], v149 offset:1024
	ds_read_b128 v[170:173], v149 offset:2048
	ds_read_b128 v[174:177], v149 offset:3072
	ds_read_b128 v[178:181], v148 offset:32768
	ds_read_b128 v[182:185], v148 offset:33792
	ds_read_b128 v[186:189], v148 offset:34816
	ds_read_b128 v[190:193], v148 offset:35840
	ds_read_b128 v[194:197], v148 offset:36864
	ds_read_b128 v[198:201], v148 offset:37888
	ds_read_b128 v[208:211], v148 offset:38912
	ds_read_b128 v[212:215], v148 offset:39936
	s_waitcnt vmcnt(8)
	s_waitcnt lgkmcnt(0)
	s_barrier
	s_setprio 1
	s_waitcnt lgkmcnt(0)
	v_mfma_f32_16x16x32_bf16 v[126:129], v[140:143], v[178:181], v[126:129]
	v_mfma_f32_16x16x32_bf16 v[118:121], v[154:157], v[178:181], v[118:121]
	v_mfma_f32_16x16x32_bf16 v[110:113], v[140:143], v[186:189], v[110:113]
	v_mfma_f32_16x16x32_bf16 v[102:105], v[154:157], v[186:189], v[102:105]
	v_mfma_f32_16x16x32_bf16 v[94:97], v[140:143], v[194:197], v[94:97]
	v_mfma_f32_16x16x32_bf16 v[86:89], v[154:157], v[194:197], v[86:89]
	v_mfma_f32_16x16x32_bf16 v[78:81], v[140:143], v[208:211], v[78:81]
	v_mfma_f32_16x16x32_bf16 v[70:73], v[154:157], v[208:211], v[70:73]
	v_mfma_f32_16x16x32_bf16 v[126:129], v[150:153], v[182:185], v[126:129]
	v_mfma_f32_16x16x32_bf16 v[118:121], v[158:161], v[182:185], v[118:121]
	v_mfma_f32_16x16x32_bf16 v[110:113], v[150:153], v[190:193], v[110:113]
	v_mfma_f32_16x16x32_bf16 v[102:105], v[158:161], v[190:193], v[102:105]
	v_mfma_f32_16x16x32_bf16 v[94:97], v[150:153], v[198:201], v[94:97]
	v_mfma_f32_16x16x32_bf16 v[86:89], v[158:161], v[198:201], v[86:89]
	v_mfma_f32_16x16x32_bf16 v[78:81], v[150:153], v[212:215], v[78:81]
	v_mfma_f32_16x16x32_bf16 v[70:73], v[158:161], v[212:215], v[70:73]
	s_setprio 0
	s_setprio 1
	v_mfma_f32_16x16x32_bf16 v[122:125], v[162:165], v[178:181], v[122:125]
	v_mfma_f32_16x16x32_bf16 v[114:117], v[170:173], v[178:181], v[114:117]
	v_mfma_f32_16x16x32_bf16 v[106:109], v[162:165], v[186:189], v[106:109]
	v_mfma_f32_16x16x32_bf16 v[98:101], v[170:173], v[186:189], v[98:101]
	v_mfma_f32_16x16x32_bf16 v[90:93], v[162:165], v[194:197], v[90:93]
	v_mfma_f32_16x16x32_bf16 v[82:85], v[170:173], v[194:197], v[82:85]
	v_mfma_f32_16x16x32_bf16 v[74:77], v[162:165], v[208:211], v[74:77]
	v_mfma_f32_16x16x32_bf16 v[66:69], v[170:173], v[208:211], v[66:69]
	v_mfma_f32_16x16x32_bf16 v[122:125], v[166:169], v[182:185], v[122:125]
	v_mfma_f32_16x16x32_bf16 v[114:117], v[174:177], v[182:185], v[114:117]
	v_mfma_f32_16x16x32_bf16 v[106:109], v[166:169], v[190:193], v[106:109]
	v_mfma_f32_16x16x32_bf16 v[98:101], v[174:177], v[190:193], v[98:101]
	v_mfma_f32_16x16x32_bf16 v[90:93], v[166:169], v[198:201], v[90:93]
	v_mfma_f32_16x16x32_bf16 v[82:85], v[174:177], v[198:201], v[82:85]
	v_mfma_f32_16x16x32_bf16 v[74:77], v[166:169], v[212:215], v[74:77]
	v_mfma_f32_16x16x32_bf16 v[66:69], v[174:177], v[212:215], v[66:69]
	s_setprio 0
	s_barrier
; #define PG8_STAGE(bufoff, gbase, voff) do { _Pragma("unroll") for (int _i = 0; _i < 2; ++_i) \
;         __builtin_amdgcn_global_load_lds((const unsigned*)((const char*)(gbase) + (voff)[_i]), (PG8_LAS unsigned*)(lds + (bufoff) + ldsw + _i * 8192), 16, 0, 0); } while (0)
; #define PG8_LDA(dst, b, h) do { _Pragma("unroll") for (int m = 0; m < 4; ++m) _Pragma("unroll") for (int k = 0; k < 2; ++k) dst[m][k] = *(const PG8_LAS bf16x8*)(lds + PG8_SA(b, h) + aoff + m * 2048 + k * 1024); } while (0)
; #define PG8_MMA(ai, bj, At, Bt) do { __builtin_amdgcn_s_setprio(1); _Pragma("unroll") for (int m = 0; m < 4; ++m) _Pragma("unroll") for (int n = 0; n < 2; ++n) _Pragma("unroll") for (int k = 0; k < 2; ++k) \
;         acc[ai][bj][m][n] = __builtin_amdgcn_mfma_f32_16x16x32_bf16(Bt[n][k], At[m][k], acc[ai][bj][m][n], 0, 0, 0); __builtin_amdgcn_s_setprio(0); } while (0)
; #define PG8_WAIT_V(n) asm volatile("s_waitcnt vmcnt(" #n ")" ::: "memory")
; #define PG8_WAIT_L(n) asm volatile("s_waitcnt lgkmcnt(" #n ")" ::: "memory")
; #define PG8_BAR __builtin_amdgcn_s_barrier()
; #define PG8_SCHED __builtin_amdgcn_sched_barrier(0)
; template <class Epi, class Sched, bool ALIGN_EPI = false, bool SP2 = false>
; __device__ __forceinline__ void gemm_phase(PG8_LAS unsigned char* lds, const Gemm g, const Sched& S, const Epi& E) {
;     ...
;             PG8_LDA(At, 1, 1); PG8_STAGE(PG8_SB(1, 0), b3, voffB); PG8_STAGE(PG8_SB(1, 1), b3 + hstepB, voffB); PG8_STAGE(PG8_SA(1, 0), a3, voffA);
;             PG8_WAIT_V(8); PG8_WAIT_L(0); PG8_BAR; PG8_MMA(1, 0, At, B0); PG8_MMA(1, 1, At, B1); PG8_BAR; PG8_SCHED;
	s_add_i32 s20, s77, s47
	v_lshl_add_u64 v[204:205], v[204:205], 0, s[22:23]
	s_mov_b32 m0, s20
	s_nop 0
	global_load_lds_dwordx4 v[204:205], off
	s_add_i32 m0, s20, 0x2000
	s_add_u32 s20, s36, 0x40080
	v_lshl_add_u64 v[204:205], v[216:217], 0, s[22:23]
	s_addc_u32 s21, s37, 0
	s_add_i32 s36, s78, s47
	global_load_lds_dwordx4 v[204:205], off
	ds_read_b128 v[178:181], v148 offset:49152
	ds_read_b128 v[182:185], v148 offset:50176
	ds_read_b128 v[186:189], v148 offset:51200
	ds_read_b128 v[190:193], v148 offset:52224
	ds_read_b128 v[194:197], v148 offset:53248
	ds_read_b128 v[198:201], v148 offset:54272
	ds_read_b128 v[208:211], v148 offset:55296
	ds_read_b128 v[212:215], v148 offset:56320
	v_lshl_add_u64 v[204:205], s[20:21], 0, v[0:1]
	s_mov_b32 m0, s36
	s_nop 0
	global_load_lds_dwordx4 v[204:205], off
	v_lshl_add_u64 v[204:205], s[20:21], 0, v[130:131]
	s_add_i32 m0, s36, 0x2000
	s_nop 0
	global_load_lds_dwordx4 v[204:205], off
	v_lshl_add_u64 v[204:205], v[218:219], 0, s[22:23]
	s_mov_b32 m0, s56
	s_nop 0
	global_load_lds_dwordx4 v[204:205], off
	v_lshl_add_u64 v[204:205], v[220:221], 0, s[22:23]
	s_mov_b32 m0, s57
	s_nop 0
	global_load_lds_dwordx4 v[204:205], off
	s_waitcnt vmcnt(8)
	s_waitcnt lgkmcnt(0)
	s_barrier
	s_setprio 1
	s_waitcnt lgkmcnt(0)
	v_mfma_f32_16x16x32_bf16 v[62:65], v[140:143], v[178:181], v[62:65]
	v_mfma_f32_16x16x32_bf16 v[54:57], v[154:157], v[178:181], v[54:57]
	v_mfma_f32_16x16x32_bf16 v[46:49], v[140:143], v[186:189], v[46:49]
	v_mfma_f32_16x16x32_bf16 v[38:41], v[154:157], v[186:189], v[38:41]
	v_mfma_f32_16x16x32_bf16 v[30:33], v[140:143], v[194:197], v[30:33]
	v_mfma_f32_16x16x32_bf16 v[22:25], v[154:157], v[194:197], v[22:25]
	v_mfma_f32_16x16x32_bf16 v[14:17], v[140:143], v[208:211], v[14:17]
	v_mfma_f32_16x16x32_bf16 v[6:9], v[154:157], v[208:211], v[6:9]
	v_mfma_f32_16x16x32_bf16 v[62:65], v[150:153], v[182:185], v[62:65]
	v_mfma_f32_16x16x32_bf16 v[54:57], v[158:161], v[182:185], v[54:57]
	v_mfma_f32_16x16x32_bf16 v[46:49], v[150:153], v[190:193], v[46:49]
	v_mfma_f32_16x16x32_bf16 v[38:41], v[158:161], v[190:193], v[38:41]
	v_mfma_f32_16x16x32_bf16 v[30:33], v[150:153], v[198:201], v[30:33]
	v_mfma_f32_16x16x32_bf16 v[22:25], v[158:161], v[198:201], v[22:25]
	v_mfma_f32_16x16x32_bf16 v[14:17], v[150:153], v[212:215], v[14:17]
	v_mfma_f32_16x16x32_bf16 v[6:9], v[158:161], v[212:215], v[6:9]
	s_setprio 0
	s_setprio 1
	v_mfma_f32_16x16x32_bf16 v[58:61], v[162:165], v[178:181], v[58:61]
	v_mfma_f32_16x16x32_bf16 v[50:53], v[170:173], v[178:181], v[50:53]
	v_mfma_f32_16x16x32_bf16 v[42:45], v[162:165], v[186:189], v[42:45]
	v_mfma_f32_16x16x32_bf16 v[34:37], v[170:173], v[186:189], v[34:37]
	v_mfma_f32_16x16x32_bf16 v[26:29], v[162:165], v[194:197], v[26:29]
	v_mfma_f32_16x16x32_bf16 v[18:21], v[170:173], v[194:197], v[18:21]
	v_mfma_f32_16x16x32_bf16 v[10:13], v[162:165], v[208:211], v[10:13]
	v_mfma_f32_16x16x32_bf16 v[2:5], v[170:173], v[208:211], v[2:5]
	v_mfma_f32_16x16x32_bf16 v[58:61], v[166:169], v[182:185], v[58:61]
	v_mfma_f32_16x16x32_bf16 v[50:53], v[174:177], v[182:185], v[50:53]
	v_mfma_f32_16x16x32_bf16 v[42:45], v[166:169], v[190:193], v[42:45]
	v_mfma_f32_16x16x32_bf16 v[34:37], v[174:177], v[190:193], v[34:37]
	v_mfma_f32_16x16x32_bf16 v[26:29], v[166:169], v[198:201], v[26:29]
	v_mfma_f32_16x16x32_bf16 v[18:21], v[174:177], v[198:201], v[18:21]
	v_mfma_f32_16x16x32_bf16 v[10:13], v[166:169], v[212:215], v[10:13]
	v_mfma_f32_16x16x32_bf16 v[2:5], v[174:177], v[212:215], v[2:5]
	s_setprio 0
	s_barrier
	s_add_i32 s76, s76, 2
	s_add_u32 s8, s8, 0x100
	s_addc_u32 s9, s9, 0
	s_add_u32 s70, s70, 0x100
	s_addc_u32 s71, s71, 0
	s_cmp_gt_u32 s76, 13
	s_cbranch_scc0 .LBB0_1212
